# proj GEMM k-loops (both layers) hand-pipelined V2: next-next tile global loads issued right behind the LDS writes of the staged tile (one full iteration of lead), pipelined LDS fragment reads with cou
# speedup vs baseline: 1.0740x; 1.0237x over previous
.LBB0_354:
	s_mov_b32 s98, 0x80
	s_mov_b32 s99, 0
	global_load_dwordx4 v[128:131], v[176:177], off
	global_load_dwordx4 v[132:135], v[184:185], off
	global_load_dwordx4 v[136:139], v[178:179], off
	global_load_dwordx4 v[140:143], v[186:187], off
	global_load_dwordx4 v[144:147], v[180:181], off
	global_load_dwordx4 v[148:151], v[188:189], off
	global_load_dwordx4 v[152:155], v[182:183], off
	global_load_dwordx4 v[156:159], v[190:191], off
	v_add3_u32 v209, v208, v164, 16
	v_add3_u32 v221, v207, v164, 16
	v_lshl_add_u64 v[176:177], v[176:177], 0, s[98:99]
	v_lshl_add_u64 v[184:185], v[184:185], 0, s[98:99]
	v_lshl_add_u64 v[178:179], v[178:179], 0, s[98:99]
	v_lshl_add_u64 v[186:187], v[186:187], 0, s[98:99]
	v_lshl_add_u64 v[180:181], v[180:181], 0, s[98:99]
	v_lshl_add_u64 v[188:189], v[188:189], 0, s[98:99]
	v_lshl_add_u64 v[182:183], v[182:183], 0, s[98:99]
	v_lshl_add_u64 v[190:191], v[190:191], 0, s[98:99]
.Lgk_p0:
	s_and_b32 s19, s8, 0x10000
	s_add_i32 s8, s8, 0x10000
	v_add3_u32 v227, v206, v221, s19
	v_add3_u32 v226, v206, v209, s19
	ds_read_b128 v[248:251], v227 offset:32768
	ds_read_b128 v[160:163], v227 offset:36864
	ds_read_b128 v[228:231], v226
	ds_read_b128 v[232:235], v226 offset:4096
	ds_read_b128 v[236:239], v226 offset:8192
	ds_read_b128 v[240:243], v226 offset:12288
	v_add3_u32 v226, v205, v209, s19
	ds_read_b128 v[244:247], v226
	v_add3_u32 v227, v205, v221, s19
	ds_read_b128 v[210:213], v227 offset:32768
	ds_read_b128 v[222:225], v227 offset:36864
	s_waitcnt lgkmcnt(6)
	v_mfma_f32_32x32x16_bf16 v[112:127], v[228:231], v[248:251], v[112:127]
	v_mfma_f32_32x32x16_bf16 v[96:111], v[228:231], v[160:163], v[96:111]
	ds_read_b128 v[228:231], v226 offset:4096
	s_waitcnt lgkmcnt(6)
	v_mfma_f32_32x32x16_bf16 v[80:95], v[232:235], v[248:251], v[80:95]
	v_mfma_f32_32x32x16_bf16 v[64:79], v[232:235], v[160:163], v[64:79]
	ds_read_b128 v[232:235], v226 offset:8192
	s_waitcnt lgkmcnt(6)
	v_mfma_f32_32x32x16_bf16 v[48:63], v[236:239], v[248:251], v[48:63]
	v_mfma_f32_32x32x16_bf16 v[32:47], v[236:239], v[160:163], v[32:47]
	ds_read_b128 v[236:239], v226 offset:12288
	s_waitcnt lgkmcnt(6)
	v_mfma_f32_32x32x16_bf16 v[16:31], v[240:243], v[248:251], v[16:31]
	v_mfma_f32_32x32x16_bf16 v[0:15], v[240:243], v[160:163], v[0:15]
	v_add3_u32 v226, v204, v209, s19
	ds_read_b128 v[240:243], v226
	v_add3_u32 v227, v204, v221, s19
	ds_read_b128 v[248:251], v227 offset:32768
	ds_read_b128 v[160:163], v227 offset:36864
	s_waitcnt lgkmcnt(6)
	v_mfma_f32_32x32x16_bf16 v[112:127], v[244:247], v[210:213], v[112:127]
	v_mfma_f32_32x32x16_bf16 v[96:111], v[244:247], v[222:225], v[96:111]
	ds_read_b128 v[244:247], v226 offset:4096
	s_waitcnt lgkmcnt(6)
	v_mfma_f32_32x32x16_bf16 v[80:95], v[228:231], v[210:213], v[80:95]
	v_mfma_f32_32x32x16_bf16 v[64:79], v[228:231], v[222:225], v[64:79]
	ds_read_b128 v[228:231], v226 offset:8192
	s_waitcnt lgkmcnt(6)
	v_mfma_f32_32x32x16_bf16 v[48:63], v[232:235], v[210:213], v[48:63]
	v_mfma_f32_32x32x16_bf16 v[32:47], v[232:235], v[222:225], v[32:47]
	ds_read_b128 v[232:235], v226 offset:12288
	s_waitcnt lgkmcnt(6)
	v_mfma_f32_32x32x16_bf16 v[16:31], v[236:239], v[210:213], v[16:31]
	v_mfma_f32_32x32x16_bf16 v[0:15], v[236:239], v[222:225], v[0:15]
	v_add3_u32 v226, v203, v209, s19
	ds_read_b128 v[236:239], v226
	v_add3_u32 v227, v203, v221, s19
	ds_read_b128 v[210:213], v227 offset:32768
	ds_read_b128 v[222:225], v227 offset:36864
	s_waitcnt lgkmcnt(6)
	v_mfma_f32_32x32x16_bf16 v[112:127], v[240:243], v[248:251], v[112:127]
	v_mfma_f32_32x32x16_bf16 v[96:111], v[240:243], v[160:163], v[96:111]
	ds_read_b128 v[240:243], v226 offset:4096
	s_waitcnt lgkmcnt(6)
	v_mfma_f32_32x32x16_bf16 v[80:95], v[244:247], v[248:251], v[80:95]
	v_mfma_f32_32x32x16_bf16 v[64:79], v[244:247], v[160:163], v[64:79]
	ds_read_b128 v[244:247], v226 offset:8192
	s_waitcnt lgkmcnt(6)
	v_mfma_f32_32x32x16_bf16 v[48:63], v[228:231], v[248:251], v[48:63]
	v_mfma_f32_32x32x16_bf16 v[32:47], v[228:231], v[160:163], v[32:47]
	ds_read_b128 v[228:231], v226 offset:12288
	s_waitcnt lgkmcnt(6)
	v_mfma_f32_32x32x16_bf16 v[16:31], v[232:235], v[248:251], v[16:31]
	v_mfma_f32_32x32x16_bf16 v[0:15], v[232:235], v[160:163], v[0:15]
	s_xor_b32 s19, s19, 0x10000
	v_add3_u32 v253, v195, s19, 16
	s_cmpk_eq_i32 s16, 0x700
	s_cselect_b64 vcc, -1, 0
	s_cbranch_scc0 .Lgk_p0_nl
	s_waitcnt vmcnt(0)
.Lgk_p0_nl:
	s_waitcnt lgkmcnt(3)
	v_mfma_f32_32x32x16_bf16 v[112:127], v[236:239], v[210:213], v[112:127]
	v_mfma_f32_32x32x16_bf16 v[96:111], v[236:239], v[222:225], v[96:111]
	s_waitcnt vmcnt(6)
	ds_write_b128 v253, v[128:131]
	ds_write_b128 v253, v[132:135] offset:32768
	s_cbranch_vccnz .Lgk_p0_s12
	global_load_dwordx4 v[128:131], v[176:177], off
	global_load_dwordx4 v[132:135], v[184:185], off
.Lgk_p0_s12:
	s_waitcnt lgkmcnt(4)
	v_mfma_f32_32x32x16_bf16 v[80:95], v[240:243], v[210:213], v[80:95]
	v_mfma_f32_32x32x16_bf16 v[64:79], v[240:243], v[222:225], v[64:79]
	s_waitcnt vmcnt(6)
	ds_write_b128 v253, v[136:139] offset:8192
	ds_write_b128 v253, v[140:143] offset:40960
	s_cbranch_vccnz .Lgk_p0_s13
	global_load_dwordx4 v[136:139], v[178:179], off
	global_load_dwordx4 v[140:143], v[186:187], off
.Lgk_p0_s13:
	s_waitcnt lgkmcnt(5)
	v_mfma_f32_32x32x16_bf16 v[48:63], v[244:247], v[210:213], v[48:63]
	v_mfma_f32_32x32x16_bf16 v[32:47], v[244:247], v[222:225], v[32:47]
	s_waitcnt vmcnt(6)
	ds_write_b128 v253, v[144:147] offset:16384
	ds_write_b128 v253, v[148:151] offset:49152
	s_cbranch_vccnz .Lgk_p0_s14
	global_load_dwordx4 v[144:147], v[180:181], off
	global_load_dwordx4 v[148:151], v[188:189], off
.Lgk_p0_s14:
	s_waitcnt lgkmcnt(6)
	v_mfma_f32_32x32x16_bf16 v[16:31], v[228:231], v[210:213], v[16:31]
	v_mfma_f32_32x32x16_bf16 v[0:15], v[228:231], v[222:225], v[0:15]
	s_waitcnt vmcnt(6)
	ds_write_b128 v253, v[152:155] offset:24576
	ds_write_b128 v253, v[156:159] offset:57344
	s_cbranch_vccnz .Lgk_p0_s15
	global_load_dwordx4 v[152:155], v[182:183], off
	global_load_dwordx4 v[156:159], v[190:191], off
.Lgk_p0_s15:
	v_lshl_add_u64 v[176:177], v[176:177], 0, s[98:99]
	v_lshl_add_u64 v[184:185], v[184:185], 0, s[98:99]
	v_lshl_add_u64 v[178:179], v[178:179], 0, s[98:99]
	v_lshl_add_u64 v[186:187], v[186:187], 0, s[98:99]
	v_lshl_add_u64 v[180:181], v[180:181], 0, s[98:99]
	v_lshl_add_u64 v[188:189], v[188:189], 0, s[98:99]
	v_lshl_add_u64 v[182:183], v[182:183], 0, s[98:99]
	v_lshl_add_u64 v[190:191], v[190:191], 0, s[98:99]
	s_add_u32 s16, s16, 0x80
	s_waitcnt lgkmcnt(0)
	s_barrier
	s_cmpk_eq_i32 s16, 0x780
	s_cbranch_scc0 .Lgk_p0
	s_add_i32 s19, s66, s92
	s_cmpk_lt_i32 s19, 0x500
	s_cselect_b64 s[16:17], -1, 0
	s_add_i32 s8, 16, 0x10000
	v_add_u32_e32 v160, s8, v206
	v_add3_u32 v184, v160, v208, v164
	ds_read_b128 v[160:163], v184
	v_add_u32_e32 v176, s29, v206
	v_add3_u32 v180, v176, v207, v164
	ds_read_b128 v[176:179], v180
	ds_read_b128 v[180:183], v180 offset:4096
	s_and_b64 vcc, exec, s[16:17]
	s_waitcnt lgkmcnt(1)
	v_mfma_f32_32x32x16_bf16 v[112:127], v[160:163], v[176:179], v[112:127]
	s_waitcnt lgkmcnt(0)
	v_mfma_f32_32x32x16_bf16 v[96:111], v[160:163], v[180:183], v[96:111]
	ds_read_b128 v[160:163], v184 offset:4096
	s_waitcnt lgkmcnt(0)
	v_mfma_f32_32x32x16_bf16 v[80:95], v[160:163], v[176:179], v[80:95]
	v_mfma_f32_32x32x16_bf16 v[64:79], v[160:163], v[180:183], v[64:79]
	ds_read_b128 v[160:163], v184 offset:8192
	s_waitcnt lgkmcnt(0)
	v_mfma_f32_32x32x16_bf16 v[48:63], v[160:163], v[176:179], v[48:63]
	v_mfma_f32_32x32x16_bf16 v[32:47], v[160:163], v[180:183], v[32:47]
	ds_read_b128 v[160:163], v184 offset:12288
	s_waitcnt lgkmcnt(0)
	v_mfma_f32_32x32x16_bf16 v[16:31], v[160:163], v[176:179], v[16:31]
	v_add_u32_e32 v176, s8, v205
	v_add3_u32 v184, v176, v208, v164
	ds_read_b128 v[176:179], v184
	v_mfma_f32_32x32x16_bf16 v[0:15], v[160:163], v[180:183], v[0:15]
	v_add_u32_e32 v160, s29, v205
	v_add3_u32 v180, v160, v207, v164
	ds_read_b128 v[160:163], v180
	ds_read_b128 v[180:183], v180 offset:4096
	s_waitcnt lgkmcnt(1)
	v_mfma_f32_32x32x16_bf16 v[112:127], v[176:179], v[160:163], v[112:127]
	s_waitcnt lgkmcnt(0)
	v_mfma_f32_32x32x16_bf16 v[96:111], v[176:179], v[180:183], v[96:111]
	ds_read_b128 v[176:179], v184 offset:4096
	s_waitcnt lgkmcnt(0)
	v_mfma_f32_32x32x16_bf16 v[80:95], v[176:179], v[160:163], v[80:95]
	v_mfma_f32_32x32x16_bf16 v[64:79], v[176:179], v[180:183], v[64:79]
	ds_read_b128 v[176:179], v184 offset:8192
	s_waitcnt lgkmcnt(0)
	v_mfma_f32_32x32x16_bf16 v[48:63], v[176:179], v[160:163], v[48:63]
	v_mfma_f32_32x32x16_bf16 v[32:47], v[176:179], v[180:183], v[32:47]
	ds_read_b128 v[176:179], v184 offset:12288
	s_waitcnt lgkmcnt(0)
	v_mfma_f32_32x32x16_bf16 v[16:31], v[176:179], v[160:163], v[16:31]
	v_add_u32_e32 v160, s8, v204
	v_add3_u32 v184, v160, v208, v164
	ds_read_b128 v[160:163], v184
	v_mfma_f32_32x32x16_bf16 v[0:15], v[176:179], v[180:183], v[0:15]
	v_add_u32_e32 v176, s29, v204
	v_add3_u32 v180, v176, v207, v164
	ds_read_b128 v[176:179], v180
	ds_read_b128 v[180:183], v180 offset:4096
	s_waitcnt lgkmcnt(1)
	v_mfma_f32_32x32x16_bf16 v[112:127], v[160:163], v[176:179], v[112:127]
	s_waitcnt lgkmcnt(0)
	v_mfma_f32_32x32x16_bf16 v[96:111], v[160:163], v[180:183], v[96:111]
	ds_read_b128 v[160:163], v184 offset:4096
	s_waitcnt lgkmcnt(0)
	v_mfma_f32_32x32x16_bf16 v[80:95], v[160:163], v[176:179], v[80:95]
	v_mfma_f32_32x32x16_bf16 v[64:79], v[160:163], v[180:183], v[64:79]
	ds_read_b128 v[160:163], v184 offset:8192
	s_waitcnt lgkmcnt(0)
	v_mfma_f32_32x32x16_bf16 v[48:63], v[160:163], v[176:179], v[48:63]
	v_mfma_f32_32x32x16_bf16 v[32:47], v[160:163], v[180:183], v[32:47]
	ds_read_b128 v[160:163], v184 offset:12288
	s_waitcnt lgkmcnt(0)
	v_mfma_f32_32x32x16_bf16 v[16:31], v[160:163], v[176:179], v[16:31]
	v_add_u32_e32 v176, s8, v203
	v_add3_u32 v184, v176, v208, v164
	ds_read_b128 v[176:179], v184
	v_mfma_f32_32x32x16_bf16 v[0:15], v[160:163], v[180:183], v[0:15]
	v_add_u32_e32 v160, s29, v203
	v_add3_u32 v164, v160, v207, v164
	ds_read_b128 v[160:163], v164
	ds_read_b128 v[180:183], v164 offset:4096
	s_waitcnt lgkmcnt(1)
	v_mfma_f32_32x32x16_bf16 v[112:127], v[176:179], v[160:163], v[112:127]
	s_waitcnt lgkmcnt(0)
	v_mfma_f32_32x32x16_bf16 v[96:111], v[176:179], v[180:183], v[96:111]
	ds_read_b128 v[176:179], v184 offset:4096
	s_waitcnt lgkmcnt(0)
	v_mfma_f32_32x32x16_bf16 v[80:95], v[176:179], v[160:163], v[80:95]
	v_mfma_f32_32x32x16_bf16 v[64:79], v[176:179], v[180:183], v[64:79]
	ds_read_b128 v[176:179], v184 offset:8192
	s_waitcnt lgkmcnt(0)
	v_mfma_f32_32x32x16_bf16 v[48:63], v[176:179], v[160:163], v[48:63]
	v_mfma_f32_32x32x16_bf16 v[32:47], v[176:179], v[180:183], v[32:47]
	ds_read_b128 v[176:179], v184 offset:12288
	s_waitcnt lgkmcnt(0)
	s_barrier
	v_mfma_f32_32x32x16_bf16 v[16:31], v[176:179], v[160:163], v[16:31]
	v_mfma_f32_32x32x16_bf16 v[0:15], v[176:179], v[180:183], v[0:15]
	s_cbranch_vccz .LBB0_357
	s_lshl_b32 s8, s19, 2
	s_and_b32 s20, s8, 0xffffff00
	s_lshl_b32 s8, s19, 19
	s_and_b32 s8, s8, 0x1f80000
	s_add_u32 s70, s22, s8
	s_addc_u32 s71, s23, 0
	s_ashr_i32 s21, s20, 31
	s_lshl_b64 s[20:21], s[20:21], 11
	s_add_u32 s20, s2, s20
	s_addc_u32 s21, s3, s21
	v_lshl_add_u64 v[152:153], s[70:71], 0, v[174:175]
	v_lshl_add_u64 v[154:155], s[20:21], 0, v[174:175]
	v_lshlrev_b64 v[128:129], 1, v[172:173]
	v_lshlrev_b64 v[136:137], 1, v[170:171]
	v_lshlrev_b64 v[144:145], 1, v[168:169]
	v_lshlrev_b64 v[156:157], 1, v[166:167]
	v_lshl_add_u64 v[130:131], v[152:153], 0, v[128:129]
	v_lshl_add_u64 v[132:133], v[154:155], 0, v[128:129]
	v_lshl_add_u64 v[138:139], v[152:153], 0, v[136:137]
	v_lshl_add_u64 v[140:141], v[154:155], 0, v[136:137]
	v_lshl_add_u64 v[146:147], v[152:153], 0, v[144:145]
	v_lshl_add_u64 v[148:149], v[154:155], 0, v[144:145]
	v_lshl_add_u64 v[152:153], v[152:153], 0, v[156:157]
	v_lshl_add_u64 v[156:157], v[154:155], 0, v[156:157]
	global_load_dwordx4 v[128:131], v[130:131], off
	s_nop 0
	global_load_dwordx4 v[132:135], v[132:133], off
	s_nop 0
	global_load_dwordx4 v[136:139], v[138:139], off
	s_nop 0
	global_load_dwordx4 v[140:143], v[140:141], off
	s_nop 0
	global_load_dwordx4 v[144:147], v[146:147], off
	s_nop 0
	global_load_dwordx4 v[148:151], v[148:149], off
	s_nop 0
	global_load_dwordx4 v[152:155], v[152:153], off
	s_nop 0
	global_load_dwordx4 v[156:159], v[156:157], off

.LBB0_737:
	s_mov_b32 s98, 0x80
	s_mov_b32 s99, 0
	global_load_dwordx4 v[128:131], v[176:177], off
	global_load_dwordx4 v[132:135], v[184:185], off
	global_load_dwordx4 v[136:139], v[178:179], off
	global_load_dwordx4 v[140:143], v[186:187], off
	global_load_dwordx4 v[144:147], v[180:181], off
	global_load_dwordx4 v[148:151], v[188:189], off
	global_load_dwordx4 v[152:155], v[182:183], off
	global_load_dwordx4 v[156:159], v[190:191], off
	v_add3_u32 v164, v205, v203, 16
	v_add3_u32 v221, v204, v203, 16
	v_lshl_add_u64 v[176:177], v[176:177], 0, s[98:99]
	v_lshl_add_u64 v[184:185], v[184:185], 0, s[98:99]
	v_lshl_add_u64 v[178:179], v[178:179], 0, s[98:99]
	v_lshl_add_u64 v[186:187], v[186:187], 0, s[98:99]
	v_lshl_add_u64 v[180:181], v[180:181], 0, s[98:99]
	v_lshl_add_u64 v[188:189], v[188:189], 0, s[98:99]
	v_lshl_add_u64 v[182:183], v[182:183], 0, s[98:99]
	v_lshl_add_u64 v[190:191], v[190:191], 0, s[98:99]
.Lgk_p1:
	s_and_b32 s13, s8, 0x10000
	s_add_i32 s8, s8, 0x10000
	v_add3_u32 v227, v209, v221, s13
	v_add3_u32 v226, v209, v164, s13
	ds_read_b128 v[248:251], v227 offset:32768
	ds_read_b128 v[160:163], v227 offset:36864
	ds_read_b128 v[228:231], v226
	ds_read_b128 v[232:235], v226 offset:4096
	ds_read_b128 v[236:239], v226 offset:8192
	ds_read_b128 v[240:243], v226 offset:12288
	v_add3_u32 v226, v208, v164, s13
	ds_read_b128 v[244:247], v226
	v_add3_u32 v227, v208, v221, s13
	ds_read_b128 v[210:213], v227 offset:32768
	ds_read_b128 v[222:225], v227 offset:36864
	s_waitcnt lgkmcnt(6)
	v_mfma_f32_32x32x16_bf16 v[112:127], v[228:231], v[248:251], v[112:127]
	v_mfma_f32_32x32x16_bf16 v[96:111], v[228:231], v[160:163], v[96:111]
	ds_read_b128 v[228:231], v226 offset:4096
	s_waitcnt lgkmcnt(6)
	v_mfma_f32_32x32x16_bf16 v[80:95], v[232:235], v[248:251], v[80:95]
	v_mfma_f32_32x32x16_bf16 v[64:79], v[232:235], v[160:163], v[64:79]
	ds_read_b128 v[232:235], v226 offset:8192
	s_waitcnt lgkmcnt(6)
	v_mfma_f32_32x32x16_bf16 v[48:63], v[236:239], v[248:251], v[48:63]
	v_mfma_f32_32x32x16_bf16 v[32:47], v[236:239], v[160:163], v[32:47]
	ds_read_b128 v[236:239], v226 offset:12288
	s_waitcnt lgkmcnt(6)
	v_mfma_f32_32x32x16_bf16 v[16:31], v[240:243], v[248:251], v[16:31]
	v_mfma_f32_32x32x16_bf16 v[0:15], v[240:243], v[160:163], v[0:15]
	v_add3_u32 v226, v207, v164, s13
	ds_read_b128 v[240:243], v226
	v_add3_u32 v227, v207, v221, s13
	ds_read_b128 v[248:251], v227 offset:32768
	ds_read_b128 v[160:163], v227 offset:36864
	s_waitcnt lgkmcnt(6)
	v_mfma_f32_32x32x16_bf16 v[112:127], v[244:247], v[210:213], v[112:127]
	v_mfma_f32_32x32x16_bf16 v[96:111], v[244:247], v[222:225], v[96:111]
	ds_read_b128 v[244:247], v226 offset:4096
	s_waitcnt lgkmcnt(6)
	v_mfma_f32_32x32x16_bf16 v[80:95], v[228:231], v[210:213], v[80:95]
	v_mfma_f32_32x32x16_bf16 v[64:79], v[228:231], v[222:225], v[64:79]
	ds_read_b128 v[228:231], v226 offset:8192
	s_waitcnt lgkmcnt(6)
	v_mfma_f32_32x32x16_bf16 v[48:63], v[232:235], v[210:213], v[48:63]
	v_mfma_f32_32x32x16_bf16 v[32:47], v[232:235], v[222:225], v[32:47]
	ds_read_b128 v[232:235], v226 offset:12288
	s_waitcnt lgkmcnt(6)
	v_mfma_f32_32x32x16_bf16 v[16:31], v[236:239], v[210:213], v[16:31]
	v_mfma_f32_32x32x16_bf16 v[0:15], v[236:239], v[222:225], v[0:15]
	v_add3_u32 v226, v206, v164, s13
	ds_read_b128 v[236:239], v226
	v_add3_u32 v227, v206, v221, s13
	ds_read_b128 v[210:213], v227 offset:32768
	ds_read_b128 v[222:225], v227 offset:36864
	s_waitcnt lgkmcnt(6)
	v_mfma_f32_32x32x16_bf16 v[112:127], v[240:243], v[248:251], v[112:127]
	v_mfma_f32_32x32x16_bf16 v[96:111], v[240:243], v[160:163], v[96:111]
	ds_read_b128 v[240:243], v226 offset:4096
	s_waitcnt lgkmcnt(6)
	v_mfma_f32_32x32x16_bf16 v[80:95], v[244:247], v[248:251], v[80:95]
	v_mfma_f32_32x32x16_bf16 v[64:79], v[244:247], v[160:163], v[64:79]
	ds_read_b128 v[244:247], v226 offset:8192
	s_waitcnt lgkmcnt(6)
	v_mfma_f32_32x32x16_bf16 v[48:63], v[228:231], v[248:251], v[48:63]
	v_mfma_f32_32x32x16_bf16 v[32:47], v[228:231], v[160:163], v[32:47]
	ds_read_b128 v[228:231], v226 offset:12288
	s_waitcnt lgkmcnt(6)
	v_mfma_f32_32x32x16_bf16 v[16:31], v[232:235], v[248:251], v[16:31]
	v_mfma_f32_32x32x16_bf16 v[0:15], v[232:235], v[160:163], v[0:15]
	s_xor_b32 s13, s13, 0x10000
	v_add3_u32 v253, v195, s13, 16
	s_cmpk_eq_i32 s10, 0x700
	s_cselect_b64 vcc, -1, 0
	s_cbranch_scc0 .Lgk_p1_nl
	s_waitcnt vmcnt(0)

.Lgk_p1_s15:
	v_lshl_add_u64 v[176:177], v[176:177], 0, s[98:99]
	v_lshl_add_u64 v[184:185], v[184:185], 0, s[98:99]
	v_lshl_add_u64 v[178:179], v[178:179], 0, s[98:99]
	v_lshl_add_u64 v[186:187], v[186:187], 0, s[98:99]
	v_lshl_add_u64 v[180:181], v[180:181], 0, s[98:99]
	v_lshl_add_u64 v[188:189], v[188:189], 0, s[98:99]
	v_lshl_add_u64 v[182:183], v[182:183], 0, s[98:99]
	v_lshl_add_u64 v[190:191], v[190:191], 0, s[98:99]
	s_add_u32 s10, s10, 0x80
	s_waitcnt lgkmcnt(0)
	s_barrier
	s_cmpk_eq_i32 s10, 0x780
	s_cbranch_scc0 .Lgk_p1
	s_add_i32 s13, s68, s92
	s_cmpk_lt_i32 s13, 0x500
	s_cselect_b64 s[10:11], -1, 0
	s_add_i32 s8, 16, 0x10000
	v_add_u32_e32 v160, s8, v209
	v_add3_u32 v164, v160, v205, v203
	ds_read_b128 v[160:163], v164
	v_add_u32_e32 v176, s23, v209
	v_add3_u32 v180, v176, v204, v203
	ds_read_b128 v[176:179], v180
	ds_read_b128 v[180:183], v180 offset:4096
	s_and_b64 vcc, exec, s[10:11]
	s_waitcnt lgkmcnt(1)
	v_mfma_f32_32x32x16_bf16 v[112:127], v[160:163], v[176:179], v[112:127]
	s_waitcnt lgkmcnt(0)
	v_mfma_f32_32x32x16_bf16 v[96:111], v[160:163], v[180:183], v[96:111]
	ds_read_b128 v[160:163], v164 offset:4096
	s_waitcnt lgkmcnt(0)
	v_mfma_f32_32x32x16_bf16 v[80:95], v[160:163], v[176:179], v[80:95]
	v_mfma_f32_32x32x16_bf16 v[64:79], v[160:163], v[180:183], v[64:79]
	ds_read_b128 v[160:163], v164 offset:8192
	s_waitcnt lgkmcnt(0)
	v_mfma_f32_32x32x16_bf16 v[48:63], v[160:163], v[176:179], v[48:63]
	v_mfma_f32_32x32x16_bf16 v[32:47], v[160:163], v[180:183], v[32:47]
	ds_read_b128 v[160:163], v164 offset:12288
	v_add_u32_e32 v164, s8, v208
	v_add3_u32 v164, v164, v205, v203
	s_waitcnt lgkmcnt(0)
	v_mfma_f32_32x32x16_bf16 v[16:31], v[160:163], v[176:179], v[16:31]
	ds_read_b128 v[176:179], v164
	v_mfma_f32_32x32x16_bf16 v[0:15], v[160:163], v[180:183], v[0:15]
	v_add_u32_e32 v160, s23, v208
	v_add3_u32 v180, v160, v204, v203
	ds_read_b128 v[160:163], v180
	ds_read_b128 v[180:183], v180 offset:4096
	s_waitcnt lgkmcnt(1)
	v_mfma_f32_32x32x16_bf16 v[112:127], v[176:179], v[160:163], v[112:127]
	s_waitcnt lgkmcnt(0)
	v_mfma_f32_32x32x16_bf16 v[96:111], v[176:179], v[180:183], v[96:111]
	ds_read_b128 v[176:179], v164 offset:4096
	s_waitcnt lgkmcnt(0)
	v_mfma_f32_32x32x16_bf16 v[80:95], v[176:179], v[160:163], v[80:95]
	v_mfma_f32_32x32x16_bf16 v[64:79], v[176:179], v[180:183], v[64:79]
	ds_read_b128 v[176:179], v164 offset:8192
	s_waitcnt lgkmcnt(0)
	v_mfma_f32_32x32x16_bf16 v[48:63], v[176:179], v[160:163], v[48:63]
	v_mfma_f32_32x32x16_bf16 v[32:47], v[176:179], v[180:183], v[32:47]
	ds_read_b128 v[176:179], v164 offset:12288
	s_waitcnt lgkmcnt(0)
	v_mfma_f32_32x32x16_bf16 v[16:31], v[176:179], v[160:163], v[16:31]
	v_add_u32_e32 v160, s8, v207
	v_add3_u32 v164, v160, v205, v203
	ds_read_b128 v[160:163], v164
	v_mfma_f32_32x32x16_bf16 v[0:15], v[176:179], v[180:183], v[0:15]
	v_add_u32_e32 v176, s23, v207
	v_add3_u32 v180, v176, v204, v203
	ds_read_b128 v[176:179], v180
	ds_read_b128 v[180:183], v180 offset:4096
	s_waitcnt lgkmcnt(1)
	v_mfma_f32_32x32x16_bf16 v[112:127], v[160:163], v[176:179], v[112:127]
	s_waitcnt lgkmcnt(0)
	v_mfma_f32_32x32x16_bf16 v[96:111], v[160:163], v[180:183], v[96:111]
	ds_read_b128 v[160:163], v164 offset:4096
	s_waitcnt lgkmcnt(0)
	v_mfma_f32_32x32x16_bf16 v[80:95], v[160:163], v[176:179], v[80:95]
	v_mfma_f32_32x32x16_bf16 v[64:79], v[160:163], v[180:183], v[64:79]
	ds_read_b128 v[160:163], v164 offset:8192
	s_waitcnt lgkmcnt(0)
	v_mfma_f32_32x32x16_bf16 v[48:63], v[160:163], v[176:179], v[48:63]
	v_mfma_f32_32x32x16_bf16 v[32:47], v[160:163], v[180:183], v[32:47]
	ds_read_b128 v[160:163], v164 offset:12288
	v_add_u32_e32 v164, s8, v206
	v_add3_u32 v164, v164, v205, v203
	s_waitcnt lgkmcnt(0)
	v_mfma_f32_32x32x16_bf16 v[16:31], v[160:163], v[176:179], v[16:31]
	ds_read_b128 v[176:179], v164
	v_mfma_f32_32x32x16_bf16 v[0:15], v[160:163], v[180:183], v[0:15]
	v_add_u32_e32 v160, s23, v206
	v_add3_u32 v180, v160, v204, v203
	ds_read_b128 v[160:163], v180
	ds_read_b128 v[180:183], v180 offset:4096
	s_waitcnt lgkmcnt(1)
	v_mfma_f32_32x32x16_bf16 v[112:127], v[176:179], v[160:163], v[112:127]
	s_waitcnt lgkmcnt(0)
	v_mfma_f32_32x32x16_bf16 v[96:111], v[176:179], v[180:183], v[96:111]
	ds_read_b128 v[176:179], v164 offset:4096
	s_waitcnt lgkmcnt(0)
	v_mfma_f32_32x32x16_bf16 v[80:95], v[176:179], v[160:163], v[80:95]
	v_mfma_f32_32x32x16_bf16 v[64:79], v[176:179], v[180:183], v[64:79]
	ds_read_b128 v[176:179], v164 offset:8192
	s_waitcnt lgkmcnt(0)
	v_mfma_f32_32x32x16_bf16 v[48:63], v[176:179], v[160:163], v[48:63]
	v_mfma_f32_32x32x16_bf16 v[32:47], v[176:179], v[180:183], v[32:47]
	ds_read_b128 v[176:179], v164 offset:12288
	s_waitcnt lgkmcnt(0)
	s_barrier
	v_mfma_f32_32x32x16_bf16 v[16:31], v[176:179], v[160:163], v[16:31]
	v_mfma_f32_32x32x16_bf16 v[0:15], v[176:179], v[180:183], v[0:15]
	s_cbranch_vccz .LBB0_740
	s_lshl_b32 s8, s13, 2
	s_and_b32 s14, s8, 0xffffff00
	s_lshl_b32 s8, s13, 19
	s_and_b32 s8, s8, 0x1f80000
	s_add_u32 s70, s16, s8
	s_addc_u32 s71, s17, 0
	s_ashr_i32 s15, s14, 31
	s_lshl_b64 s[14:15], s[14:15], 11
	s_add_u32 s14, s2, s14
	s_addc_u32 s15, s3, s15
	v_lshl_add_u64 v[152:153], s[70:71], 0, v[174:175]
	v_lshl_add_u64 v[154:155], s[14:15], 0, v[174:175]
	v_lshlrev_b64 v[128:129], 1, v[166:167]
	v_lshlrev_b64 v[136:137], 1, v[168:169]
	v_lshlrev_b64 v[144:145], 1, v[170:171]
	v_lshlrev_b64 v[156:157], 1, v[172:173]
	v_lshl_add_u64 v[130:131], v[152:153], 0, v[128:129]
	v_lshl_add_u64 v[132:133], v[154:155], 0, v[128:129]
	v_lshl_add_u64 v[138:139], v[152:153], 0, v[136:137]
	v_lshl_add_u64 v[140:141], v[154:155], 0, v[136:137]
	v_lshl_add_u64 v[146:147], v[152:153], 0, v[144:145]
	v_lshl_add_u64 v[148:149], v[154:155], 0, v[144:145]
	v_lshl_add_u64 v[152:153], v[152:153], 0, v[156:157]
	v_lshl_add_u64 v[156:157], v[154:155], 0, v[156:157]
	global_load_dwordx4 v[128:131], v[130:131], off
	s_nop 0
	global_load_dwordx4 v[132:135], v[132:133], off
	s_nop 0
	global_load_dwordx4 v[136:139], v[138:139], off
	s_nop 0
	global_load_dwordx4 v[140:143], v[140:141], off
	s_nop 0
	global_load_dwordx4 v[144:147], v[146:147], off
	s_nop 0
	global_load_dwordx4 v[148:151], v[148:149], off
	s_nop 0
	global_load_dwordx4 v[152:155], v[152:153], off
	s_nop 0
	global_load_dwordx4 v[156:159], v[156:157], off
